# stack on the best version: hand-written phase-3 strip (v^T / decay rows through LDS), phase-6 tile groups 8 rows high (12 instead of 18 panel slices beyond L2 per K-tile), scalar-base LDS-DMA addressi
# baseline (speedup 1.0000x reference)
; __device__ __forceinline__ int tid_of_(int wave) { return wave * 64 + lane_id_(); }
; template <int NDV>
; __device__ __forceinline__ void ph_g12_strip(Frame& F, int id) {
;     int tid_ = tid_of_(F.wave); asm volatile("" : "+v"(tid_)); const int lane = tid_ & 63, fr = lane & 15, fq = lane >> 4, w = F.wave;
;     const unsigned l16 = (unsigned)lane * 16u;
;     const unsigned sto = (unsigned)(((fq >> 1) * 16 + fr) * 16 + (fq & 1) * 8);
;     constexpr int PH = 32 / NDV;
;     const int seq = id / (NH * PH), h = (id / PH) % NH, sl = id % PH;
;     const int ci0 = seq * 128;
;     const unsigned char* vb0 = F.ws + WS_VT + (((size_t)ci0 * 128 + h * 32 + NDV * sl) * 2) * 1024;
;     const unsigned char* kb0 = F.ws + WS_KINT + (((size_t)ci0 * 64 + h * 16 + 2 * w) * 2) * 1024;
;     const float* Ap0 = (const float*)(F.ws + WS_AOUT) + (size_t)ci0 * GK + h * DK + 32 * w + 4 * fq;
;     f32x4 S[2][NDV];
; #pragma unroll
;     for (int j = 0; j < 2; ++j)
; #pragma unroll
;         for (int n = 0; n < NDV; ++n) S[j][n] = (f32x4){0.f, 0.f, 0.f, 0.f};
;     bf16x8 rk[4][2][2], rv[4][NDV][2]; f32x4 rA[4][2];
;     ...
;     G12_LOAD(0, 0); G12_LOAD(1, 1); G12_LOAD(2, 2); G12_LOAD(3, 3);
.LBB0_479:
	s_and_b64 vcc, exec, s[0:1]
	s_cbranch_vccz .LBB0_474
	v_readlane_b32 s79, v255, 41
	s_lshr_b32 s58, s78, 7
	s_bfe_u32 s59, s78, 0x20005
	s_and_b32 s60, s78, 31
	v_and_b32_e32 v236, 15, v166
	v_lshrrev_b32_e32 v237, 4, v166
	v_lshlrev_b32_e32 v248, 4, v166
	s_lshl_b32 s0, s79, 7
	v_lshl_add_u32 v249, v237, 4, s0
	v_lshrrev_b32_e32 v238, 1, v237
	v_and_b32_e32 v239, 1, v237
	v_lshlrev_b32_e32 v251, 8, v238
	v_lshl_add_u32 v251, v236, 4, v251
	v_lshl_add_u32 v251, v239, 3, v251
	s_lshl_b32 s0, s58, 24
	s_lshl_b32 s1, s59, 15
	s_add_u32 s0, s0, s1
	s_lshl_b32 s1, s79, 12
	s_add_u32 s0, s0, s1
	s_add_u32 s0, s0, 0x51c00000
	s_add_u32 s28, s34, s0
	s_addc_u32 s29, s35, 0
	s_mov_b32 s0, 0x100000
	s_mov_b32 s1, 0x3d400000
	s_cmp_lg_u32 s58, 0
	s_cselect_b32 s0, s1, s0
	s_lshl_b32 s1, s59, 18
	s_add_u32 s0, s0, s1
	s_lshl_b32 s1, s60, 13
	s_add_u32 s0, s0, s1
	s_lshl_b32 s1, s79, 10
	s_add_u32 s0, s0, s1
	s_add_u32 s40, s34, s0
	s_addc_u32 s41, s35, 0
	s_lshl_b32 s0, s58, 25
	s_lshl_b32 s1, s59, 16
	s_add_u32 s0, s0, s1
	s_lshl_b32 s1, s60, 11
	s_add_u32 s0, s0, s1
	s_add_u32 s80, s0, 0x4d400000
	s_lshl_b32 s0, s58, 19
	s_lshl_b32 s1, s59, 10
	s_add_u32 s0, s0, s1
	s_add_u32 s81, s0, 0x47c00000
	s_mul_i32 s82, s79, 3
	s_add_i32 s0, s82, 0
	s_cmp_lt_u32 s0, 16
	s_cbranch_scc0 .Lstrip2_a0
	s_lshr_b32 s1, s0, 1
	s_lshl_b32 s1, s1, 18
	s_and_b32 s42, s0, 1
	s_lshl_b32 s42, s42, 10
	s_add_u32 s1, s1, s42
	s_add_u32 s30, s80, s1
	s_mov_b32 s37, 0x200000
	s_lshl_b32 s42, s0, 10
	s_branch .Lstrip2_d0

; __device__ __forceinline__ unsigned pk2(float lo, float hi) { return pg8::cvt_pk_bf16(lo, hi); }
; template <int NDV>
; __device__ __forceinline__ void ph_g12_strip(Frame& F, int id) {
;     ...
;     f32x4 S[2][NDV];
; #pragma unroll
;     for (int j = 0; j < 2; ++j)
; #pragma unroll
;         for (int n = 0; n < NDV; ++n) S[j][n] = (f32x4){0.f, 0.f, 0.f, 0.f};
;     bf16x8 rk[4][2][2], rv[4][NDV][2]; f32x4 rA[4][2];
;     ...
;     G12_LOAD(0, 0); G12_LOAD(1, 1); G12_LOAD(2, 2); G12_LOAD(3, 3);
; #pragma unroll 1
;     for (int c0 = 0; c0 < 128; c0 += 4) {
; #pragma unroll
;         for (int u = 0; u < 4; ++u) {
;             const int cc = c0 + u;
;             unsigned char* slot = (unsigned char*)slot_ptr(F, ci0 + cc, h);
;             f32x4 D[2][NDV];
; #pragma unroll
;             for (int j = 0; j < 2; ++j)
; #pragma unroll
;                 for (int n = 0; n < NDV; ++n) { D[j][n] = (f32x4){0.f, 0.f, 0.f, 0.f};
; #pragma unroll
;                     for (int ks = 0; ks < 2; ++ks) D[j][n] = __builtin_amdgcn_mfma_f32_16x16x32_bf16(rk[u][j][ks], rv[u][n][ks], D[j][n], 0, 0, 0); }
; #pragma unroll
;             for (int j = 0; j < 2; ++j) { const int t = 2 * w + j, qd = t >> 2, c = t & 3; const f32x4 A = rA[u][j];
; #pragma unroll
;                 for (int n = 0; n < NDV; ++n) { const int nn = NDV * sl + n; v2u o; o.x = pk2(S[j][n][0], S[j][n][1]); o.y = pk2(S[j][n][2], S[j][n][3]);
;                     *(v2u*)(slot + (size_t)((nn * 8 + 2 * qd + (c >> 1)) * 64 + 2 * (c & 1) * 16) * 16 + sto) = o;
;                     S[j][n] = (S[j][n] + D[j][n]) * A; } }
;             if (cc + 4 < 128) G12_LOAD(u, cc + 4);
.Lstrip2_d2:
	v_mov_b32_e32 v0, 0
	v_mov_b32_e32 v1, 0
	v_mov_b32_e32 v2, 0
	v_mov_b32_e32 v3, 0
	v_mov_b32_e32 v4, 0
	v_mov_b32_e32 v5, 0
	v_mov_b32_e32 v6, 0
	v_mov_b32_e32 v7, 0
	v_add_u32_e32 v236, s30, v248
	s_add_i32 m0, s42, 0x0
	s_add_u32 s30, s30, s37
	global_load_lds_dwordx4 v236, s[34:35]
	v_add_u32_e32 v236, s31, v248
	s_add_i32 m0, s43, 0x0
	s_add_u32 s31, s31, s38
	global_load_lds_dwordx4 v236, s[34:35]
	v_add_u32_e32 v236, s36, v248
	s_add_i32 m0, s61, 0x0
	s_add_u32 s36, s36, s39
	global_load_lds_dwordx4 v236, s[34:35]
	global_load_dwordx4 v[16:19], v248, s[28:29]
	global_load_dwordx4 v[20:23], v248, s[28:29] offset:1024
	global_load_dwordx4 v[24:27], v248, s[28:29] offset:2048
	global_load_dwordx4 v[28:31], v248, s[28:29] offset:3072
	s_add_u32 s28, s28, 0x20000
	s_addc_u32 s29, s29, 0
	global_load_dwordx4 v[32:35], v248, s[28:29]
	global_load_dwordx4 v[36:39], v248, s[28:29] offset:1024
	global_load_dwordx4 v[40:43], v248, s[28:29] offset:2048
	global_load_dwordx4 v[44:47], v248, s[28:29] offset:3072
	s_add_u32 s28, s28, 0x20000
	s_addc_u32 s29, s29, 0
	global_load_dwordx4 v[48:51], v248, s[28:29]
	global_load_dwordx4 v[52:55], v248, s[28:29] offset:1024
	global_load_dwordx4 v[56:59], v248, s[28:29] offset:2048
	global_load_dwordx4 v[60:63], v248, s[28:29] offset:3072
	s_add_u32 s28, s28, 0x20000
	s_addc_u32 s29, s29, 0
	s_movk_i32 s8, 8
	s_waitcnt vmcnt(0)
.Lstrip2_loop:
	s_barrier
	v_add_u32_e32 v236, s30, v248
	s_add_i32 m0, s42, 0x6000
	s_add_u32 s30, s30, s37
	global_load_lds_dwordx4 v236, s[34:35]
	v_add_u32_e32 v236, s31, v248
	s_add_i32 m0, s43, 0x6000
	s_add_u32 s31, s31, s38
	global_load_lds_dwordx4 v236, s[34:35]
	v_add_u32_e32 v236, s36, v248
	s_add_i32 m0, s61, 0x6000
	s_add_u32 s36, s36, s39
	global_load_lds_dwordx4 v236, s[34:35]
	ds_read_b128 v[200:203], v248 offset:0
	ds_read_b128 v[204:207], v248 offset:1024
	ds_read_b128 v[208:211], v249 offset:16384
	ds_read_b128 v[212:215], v249 offset:16448
	global_load_dwordx4 v[64:67], v248, s[28:29]
	global_load_dwordx4 v[68:71], v248, s[28:29] offset:1024
	global_load_dwordx4 v[72:75], v248, s[28:29] offset:2048
	global_load_dwordx4 v[76:79], v248, s[28:29] offset:3072
	s_add_u32 s28, s28, 0x20000
	s_addc_u32 s29, s29, 0
	ds_read_b128 v[216:219], v248 offset:2048
	ds_read_b128 v[220:223], v248 offset:3072
	ds_read_b128 v[224:227], v249 offset:17408
	ds_read_b128 v[228:231], v249 offset:17472
	s_waitcnt vmcnt(21)
	s_waitcnt lgkmcnt(4)
	v_mfma_f32_16x16x32_bf16 v[8:11], v[16:19], v[200:203], 0
	v_mfma_f32_16x16x32_bf16 v[12:15], v[24:27], v[200:203], 0
	v_mfma_f32_16x16x32_bf16 v[8:11], v[20:23], v[204:207], v[8:11]
	v_mfma_f32_16x16x32_bf16 v[12:15], v[28:31], v[204:207], v[12:15]
	v_cvt_pk_bf16_f32 v232, v0, v1
	v_cvt_pk_bf16_f32 v233, v2, v3
	v_cvt_pk_bf16_f32 v234, v4, v5
	v_cvt_pk_bf16_f32 v235, v6, v7
	global_store_dwordx2 v251, v[232:233], s[40:41]
	global_store_dwordx2 v251, v[234:235], s[40:41] offset:512
	s_add_u32 s40, s40, 0x100000
	s_addc_u32 s41, s41, 0
	s_nop 7
	v_add_f32_e32 v0, v0, v8
	v_add_f32_e32 v1, v1, v9
	v_add_f32_e32 v2, v2, v10
	v_add_f32_e32 v3, v3, v11
	v_add_f32_e32 v4, v4, v12
	v_add_f32_e32 v5, v5, v13
	v_add_f32_e32 v6, v6, v14
	v_add_f32_e32 v7, v7, v15
	v_mul_f32_e32 v0, v0, v208
	v_mul_f32_e32 v1, v1, v209
	v_mul_f32_e32 v2, v2, v210
	v_mul_f32_e32 v3, v3, v211
	v_mul_f32_e32 v4, v4, v212
	v_mul_f32_e32 v5, v5, v213
	v_mul_f32_e32 v6, v6, v214
	v_mul_f32_e32 v7, v7, v215
	global_load_dwordx4 v[16:19], v248, s[28:29]
	global_load_dwordx4 v[20:23], v248, s[28:29] offset:1024
	global_load_dwordx4 v[24:27], v248, s[28:29] offset:2048
	global_load_dwordx4 v[28:31], v248, s[28:29] offset:3072
	s_add_u32 s28, s28, 0x20000
	s_addc_u32 s29, s29, 0
	ds_read_b128 v[200:203], v248 offset:4096
	ds_read_b128 v[204:207], v248 offset:5120
	ds_read_b128 v[208:211], v249 offset:18432
	ds_read_b128 v[212:215], v249 offset:18496
	s_waitcnt vmcnt(21)
	s_waitcnt lgkmcnt(4)
	v_mfma_f32_16x16x32_bf16 v[8:11], v[32:35], v[216:219], 0
	v_mfma_f32_16x16x32_bf16 v[12:15], v[40:43], v[216:219], 0
	v_mfma_f32_16x16x32_bf16 v[8:11], v[36:39], v[220:223], v[8:11]
	v_mfma_f32_16x16x32_bf16 v[12:15], v[44:47], v[220:223], v[12:15]
	v_cvt_pk_bf16_f32 v232, v0, v1
	v_cvt_pk_bf16_f32 v233, v2, v3
	v_cvt_pk_bf16_f32 v234, v4, v5
	v_cvt_pk_bf16_f32 v235, v6, v7
	global_store_dwordx2 v251, v[232:233], s[40:41]
	global_store_dwordx2 v251, v[234:235], s[40:41] offset:512
	s_add_u32 s40, s40, 0x100000
	s_addc_u32 s41, s41, 0
	s_nop 7
	v_add_f32_e32 v0, v0, v8
	v_add_f32_e32 v1, v1, v9
	v_add_f32_e32 v2, v2, v10
	v_add_f32_e32 v3, v3, v11
	v_add_f32_e32 v4, v4, v12
	v_add_f32_e32 v5, v5, v13
	v_add_f32_e32 v6, v6, v14
	v_add_f32_e32 v7, v7, v15
	v_mul_f32_e32 v0, v0, v224
	v_mul_f32_e32 v1, v1, v225
	v_mul_f32_e32 v2, v2, v226
	v_mul_f32_e32 v3, v3, v227
	v_mul_f32_e32 v4, v4, v228
	v_mul_f32_e32 v5, v5, v229
	v_mul_f32_e32 v6, v6, v230
	v_mul_f32_e32 v7, v7, v231
	global_load_dwordx4 v[32:35], v248, s[28:29]
	global_load_dwordx4 v[36:39], v248, s[28:29] offset:1024
	global_load_dwordx4 v[40:43], v248, s[28:29] offset:2048
	global_load_dwordx4 v[44:47], v248, s[28:29] offset:3072
	s_add_u32 s28, s28, 0x20000
	s_addc_u32 s29, s29, 0
	ds_read_b128 v[216:219], v248 offset:6144
	ds_read_b128 v[220:223], v248 offset:7168
	ds_read_b128 v[224:227], v249 offset:19456
	ds_read_b128 v[228:231], v249 offset:19520
	s_waitcnt vmcnt(21)
	s_waitcnt lgkmcnt(4)
; __device__ __forceinline__ unsigned pk2(float lo, float hi) { return pg8::cvt_pk_bf16(lo, hi); }
; template <int NDV>
; __device__ __forceinline__ void ph_g12_strip(Frame& F, int id) {
;     ...
;     for (int c0 = 0; c0 < 128; c0 += 4) {
; #pragma unroll
;         for (int u = 0; u < 4; ++u) {
;             const int cc = c0 + u;
;             unsigned char* slot = (unsigned char*)slot_ptr(F, ci0 + cc, h);
;             f32x4 D[2][NDV];
; #pragma unroll
;             for (int j = 0; j < 2; ++j)
; #pragma unroll
;                 for (int n = 0; n < NDV; ++n) { D[j][n] = (f32x4){0.f, 0.f, 0.f, 0.f};
; #pragma unroll
;                     for (int ks = 0; ks < 2; ++ks) D[j][n] = __builtin_amdgcn_mfma_f32_16x16x32_bf16(rk[u][j][ks], rv[u][n][ks], D[j][n], 0, 0, 0); }
; #pragma unroll
;             for (int j = 0; j < 2; ++j) { const int t = 2 * w + j, qd = t >> 2, c = t & 3; const f32x4 A = rA[u][j];
; #pragma unroll
;                 for (int n = 0; n < NDV; ++n) { const int nn = NDV * sl + n; v2u o; o.x = pk2(S[j][n][0], S[j][n][1]); o.y = pk2(S[j][n][2], S[j][n][3]);
;                     *(v2u*)(slot + (size_t)((nn * 8 + 2 * qd + (c >> 1)) * 64 + 2 * (c & 1) * 16) * 16 + sto) = o;
;                     S[j][n] = (S[j][n] + D[j][n]) * A; } }
;             if (cc + 4 < 128) G12_LOAD(u, cc + 4);
	v_mfma_f32_16x16x32_bf16 v[8:11], v[48:51], v[200:203], 0
	v_mfma_f32_16x16x32_bf16 v[12:15], v[56:59], v[200:203], 0
	v_mfma_f32_16x16x32_bf16 v[8:11], v[52:55], v[204:207], v[8:11]
	v_mfma_f32_16x16x32_bf16 v[12:15], v[60:63], v[204:207], v[12:15]
	v_cvt_pk_bf16_f32 v232, v0, v1
	v_cvt_pk_bf16_f32 v233, v2, v3
	v_cvt_pk_bf16_f32 v234, v4, v5
	v_cvt_pk_bf16_f32 v235, v6, v7
	global_store_dwordx2 v251, v[232:233], s[40:41]
	global_store_dwordx2 v251, v[234:235], s[40:41] offset:512
	s_add_u32 s40, s40, 0x100000
	s_addc_u32 s41, s41, 0
	s_nop 7
	v_add_f32_e32 v0, v0, v8
	v_add_f32_e32 v1, v1, v9
	v_add_f32_e32 v2, v2, v10
	v_add_f32_e32 v3, v3, v11
	v_add_f32_e32 v4, v4, v12
	v_add_f32_e32 v5, v5, v13
	v_add_f32_e32 v6, v6, v14
	v_add_f32_e32 v7, v7, v15
	v_mul_f32_e32 v0, v0, v208
	v_mul_f32_e32 v1, v1, v209
	v_mul_f32_e32 v2, v2, v210
	v_mul_f32_e32 v3, v3, v211
	v_mul_f32_e32 v4, v4, v212
	v_mul_f32_e32 v5, v5, v213
	v_mul_f32_e32 v6, v6, v214
	v_mul_f32_e32 v7, v7, v215
	global_load_dwordx4 v[48:51], v248, s[28:29]
	global_load_dwordx4 v[52:55], v248, s[28:29] offset:1024
	global_load_dwordx4 v[56:59], v248, s[28:29] offset:2048
	global_load_dwordx4 v[60:63], v248, s[28:29] offset:3072
	s_add_u32 s28, s28, 0x20000
	s_addc_u32 s29, s29, 0
	ds_read_b128 v[200:203], v248 offset:8192
	ds_read_b128 v[204:207], v248 offset:9216
	ds_read_b128 v[208:211], v249 offset:20480
	ds_read_b128 v[212:215], v249 offset:20544
	s_waitcnt vmcnt(18)
	s_waitcnt lgkmcnt(4)
	v_mfma_f32_16x16x32_bf16 v[8:11], v[64:67], v[216:219], 0
	v_mfma_f32_16x16x32_bf16 v[12:15], v[72:75], v[216:219], 0
	v_mfma_f32_16x16x32_bf16 v[8:11], v[68:71], v[220:223], v[8:11]
	v_mfma_f32_16x16x32_bf16 v[12:15], v[76:79], v[220:223], v[12:15]
	v_cvt_pk_bf16_f32 v232, v0, v1
	v_cvt_pk_bf16_f32 v233, v2, v3
	v_cvt_pk_bf16_f32 v234, v4, v5
	v_cvt_pk_bf16_f32 v235, v6, v7
	global_store_dwordx2 v251, v[232:233], s[40:41]
	global_store_dwordx2 v251, v[234:235], s[40:41] offset:512
	s_add_u32 s40, s40, 0x100000
	s_addc_u32 s41, s41, 0
	s_nop 7
	v_add_f32_e32 v0, v0, v8
	v_add_f32_e32 v1, v1, v9
	v_add_f32_e32 v2, v2, v10
	v_add_f32_e32 v3, v3, v11
	v_add_f32_e32 v4, v4, v12
	v_add_f32_e32 v5, v5, v13
	v_add_f32_e32 v6, v6, v14
	v_add_f32_e32 v7, v7, v15
	v_mul_f32_e32 v0, v0, v224
	v_mul_f32_e32 v1, v1, v225
	v_mul_f32_e32 v2, v2, v226
	v_mul_f32_e32 v3, v3, v227
	v_mul_f32_e32 v4, v4, v228
	v_mul_f32_e32 v5, v5, v229
	v_mul_f32_e32 v6, v6, v230
	v_mul_f32_e32 v7, v7, v231
	global_load_dwordx4 v[64:67], v248, s[28:29]
	global_load_dwordx4 v[68:71], v248, s[28:29] offset:1024
	global_load_dwordx4 v[72:75], v248, s[28:29] offset:2048
	global_load_dwordx4 v[76:79], v248, s[28:29] offset:3072
	s_add_u32 s28, s28, 0x20000
	s_addc_u32 s29, s29, 0
	ds_read_b128 v[216:219], v248 offset:10240
	ds_read_b128 v[220:223], v248 offset:11264
	ds_read_b128 v[224:227], v249 offset:21504
	ds_read_b128 v[228:231], v249 offset:21568
	s_waitcnt vmcnt(18)
	s_waitcnt lgkmcnt(4)
	v_mfma_f32_16x16x32_bf16 v[8:11], v[16:19], v[200:203], 0
	v_mfma_f32_16x16x32_bf16 v[12:15], v[24:27], v[200:203], 0
	v_mfma_f32_16x16x32_bf16 v[8:11], v[20:23], v[204:207], v[8:11]
	v_mfma_f32_16x16x32_bf16 v[12:15], v[28:31], v[204:207], v[12:15]
	v_cvt_pk_bf16_f32 v232, v0, v1
	v_cvt_pk_bf16_f32 v233, v2, v3
	v_cvt_pk_bf16_f32 v234, v4, v5
	v_cvt_pk_bf16_f32 v235, v6, v7
	global_store_dwordx2 v251, v[232:233], s[40:41]
	global_store_dwordx2 v251, v[234:235], s[40:41] offset:512
	s_add_u32 s40, s40, 0x100000
	s_addc_u32 s41, s41, 0
	s_nop 7
	v_add_f32_e32 v0, v0, v8
	v_add_f32_e32 v1, v1, v9
	v_add_f32_e32 v2, v2, v10
	v_add_f32_e32 v3, v3, v11
	v_add_f32_e32 v4, v4, v12
	v_add_f32_e32 v5, v5, v13
	v_add_f32_e32 v6, v6, v14
	v_add_f32_e32 v7, v7, v15
	v_mul_f32_e32 v0, v0, v208
	v_mul_f32_e32 v1, v1, v209
	v_mul_f32_e32 v2, v2, v210
	v_mul_f32_e32 v3, v3, v211
	v_mul_f32_e32 v4, v4, v212
	v_mul_f32_e32 v5, v5, v213
	v_mul_f32_e32 v6, v6, v214
	v_mul_f32_e32 v7, v7, v215
	global_load_dwordx4 v[16:19], v248, s[28:29]
	global_load_dwordx4 v[20:23], v248, s[28:29] offset:1024
	global_load_dwordx4 v[24:27], v248, s[28:29] offset:2048
	global_load_dwordx4 v[28:31], v248, s[28:29] offset:3072
	s_add_u32 s28, s28, 0x20000
	s_addc_u32 s29, s29, 0
	ds_read_b128 v[200:203], v248 offset:12288
	ds_read_b128 v[204:207], v248 offset:13312
	ds_read_b128 v[208:211], v249 offset:22528
	ds_read_b128 v[212:215], v249 offset:22592
	s_waitcnt vmcnt(18)
	s_waitcnt lgkmcnt(4)
	v_mfma_f32_16x16x32_bf16 v[8:11], v[32:35], v[216:219], 0
	v_mfma_f32_16x16x32_bf16 v[12:15], v[40:43], v[216:219], 0
	v_mfma_f32_16x16x32_bf16 v[8:11], v[36:39], v[220:223], v[8:11]
	v_mfma_f32_16x16x32_bf16 v[12:15], v[44:47], v[220:223], v[12:15]
	v_cvt_pk_bf16_f32 v232, v0, v1
	v_cvt_pk_bf16_f32 v233, v2, v3
	v_cvt_pk_bf16_f32 v234, v4, v5
	v_cvt_pk_bf16_f32 v235, v6, v7
	global_store_dwordx2 v251, v[232:233], s[40:41]
	global_store_dwordx2 v251, v[234:235], s[40:41] offset:512
	s_add_u32 s40, s40, 0x100000
	s_addc_u32 s41, s41, 0
	s_nop 7
	v_add_f32_e32 v0, v0, v8
	v_add_f32_e32 v1, v1, v9
	v_add_f32_e32 v2, v2, v10
	v_add_f32_e32 v3, v3, v11
	v_add_f32_e32 v4, v4, v12
	v_add_f32_e32 v5, v5, v13
	v_add_f32_e32 v6, v6, v14
	v_add_f32_e32 v7, v7, v15
	v_mul_f32_e32 v0, v0, v224
	v_mul_f32_e32 v1, v1, v225
	v_mul_f32_e32 v2, v2, v226
	v_mul_f32_e32 v3, v3, v227
	v_mul_f32_e32 v4, v4, v228
	v_mul_f32_e32 v5, v5, v229
	v_mul_f32_e32 v6, v6, v230
	v_mul_f32_e32 v7, v7, v231
	global_load_dwordx4 v[32:35], v248, s[28:29]
	global_load_dwordx4 v[36:39], v248, s[28:29] offset:1024
	global_load_dwordx4 v[40:43], v248, s[28:29] offset:2048
	global_load_dwordx4 v[44:47], v248, s[28:29] offset:3072
	s_add_u32 s28, s28, 0x20000
	s_addc_u32 s29, s29, 0
	ds_read_b128 v[216:219], v248 offset:14336
	ds_read_b128 v[220:223], v248 offset:15360
	ds_read_b128 v[224:227], v249 offset:23552
	ds_read_b128 v[228:231], v249 offset:23616
	s_waitcnt vmcnt(18)
; __device__ __forceinline__ unsigned pk2(float lo, float hi) { return pg8::cvt_pk_bf16(lo, hi); }
; template <int NDV>
; __device__ __forceinline__ void ph_g12_strip(Frame& F, int id) {
;     ...
;     for (int c0 = 0; c0 < 128; c0 += 4) {
; #pragma unroll
;         for (int u = 0; u < 4; ++u) {
;             const int cc = c0 + u;
;             unsigned char* slot = (unsigned char*)slot_ptr(F, ci0 + cc, h);
;             f32x4 D[2][NDV];
; #pragma unroll
;             for (int j = 0; j < 2; ++j)
; #pragma unroll
;                 for (int n = 0; n < NDV; ++n) { D[j][n] = (f32x4){0.f, 0.f, 0.f, 0.f};
; #pragma unroll
;                     for (int ks = 0; ks < 2; ++ks) D[j][n] = __builtin_amdgcn_mfma_f32_16x16x32_bf16(rk[u][j][ks], rv[u][n][ks], D[j][n], 0, 0, 0); }
; #pragma unroll
;             for (int j = 0; j < 2; ++j) { const int t = 2 * w + j, qd = t >> 2, c = t & 3; const f32x4 A = rA[u][j];
; #pragma unroll
;                 for (int n = 0; n < NDV; ++n) { const int nn = NDV * sl + n; v2u o; o.x = pk2(S[j][n][0], S[j][n][1]); o.y = pk2(S[j][n][2], S[j][n][3]);
;                     *(v2u*)(slot + (size_t)((nn * 8 + 2 * qd + (c >> 1)) * 64 + 2 * (c & 1) * 16) * 16 + sto) = o;
;                     S[j][n] = (S[j][n] + D[j][n]) * A; } }
;             if (cc + 4 < 128) G12_LOAD(u, cc + 4);
	s_waitcnt lgkmcnt(4)
	v_mfma_f32_16x16x32_bf16 v[8:11], v[48:51], v[200:203], 0
	v_mfma_f32_16x16x32_bf16 v[12:15], v[56:59], v[200:203], 0
	v_mfma_f32_16x16x32_bf16 v[8:11], v[52:55], v[204:207], v[8:11]
	v_mfma_f32_16x16x32_bf16 v[12:15], v[60:63], v[204:207], v[12:15]
	v_cvt_pk_bf16_f32 v232, v0, v1
	v_cvt_pk_bf16_f32 v233, v2, v3
	v_cvt_pk_bf16_f32 v234, v4, v5
	v_cvt_pk_bf16_f32 v235, v6, v7
	global_store_dwordx2 v251, v[232:233], s[40:41]
	global_store_dwordx2 v251, v[234:235], s[40:41] offset:512
	s_add_u32 s40, s40, 0x100000
	s_addc_u32 s41, s41, 0
	s_nop 7
	v_add_f32_e32 v0, v0, v8
	v_add_f32_e32 v1, v1, v9
	v_add_f32_e32 v2, v2, v10
	v_add_f32_e32 v3, v3, v11
	v_add_f32_e32 v4, v4, v12
	v_add_f32_e32 v5, v5, v13
	v_add_f32_e32 v6, v6, v14
	v_add_f32_e32 v7, v7, v15
	v_mul_f32_e32 v0, v0, v208
	v_mul_f32_e32 v1, v1, v209
	v_mul_f32_e32 v2, v2, v210
	v_mul_f32_e32 v3, v3, v211
	v_mul_f32_e32 v4, v4, v212
	v_mul_f32_e32 v5, v5, v213
	v_mul_f32_e32 v6, v6, v214
	v_mul_f32_e32 v7, v7, v215
	global_load_dwordx4 v[48:51], v248, s[28:29]
	global_load_dwordx4 v[52:55], v248, s[28:29] offset:1024
	global_load_dwordx4 v[56:59], v248, s[28:29] offset:2048
	global_load_dwordx4 v[60:63], v248, s[28:29] offset:3072
	s_add_u32 s28, s28, 0x20000
	s_addc_u32 s29, s29, 0
	s_waitcnt vmcnt(18)
	s_waitcnt lgkmcnt(0)
	v_mfma_f32_16x16x32_bf16 v[8:11], v[64:67], v[216:219], 0
	v_mfma_f32_16x16x32_bf16 v[12:15], v[72:75], v[216:219], 0
	v_mfma_f32_16x16x32_bf16 v[8:11], v[68:71], v[220:223], v[8:11]
	v_mfma_f32_16x16x32_bf16 v[12:15], v[76:79], v[220:223], v[12:15]
	v_cvt_pk_bf16_f32 v232, v0, v1
	v_cvt_pk_bf16_f32 v233, v2, v3
	v_cvt_pk_bf16_f32 v234, v4, v5
	v_cvt_pk_bf16_f32 v235, v6, v7
	global_store_dwordx2 v251, v[232:233], s[40:41]
	global_store_dwordx2 v251, v[234:235], s[40:41] offset:512
	s_add_u32 s40, s40, 0x100000
	s_addc_u32 s41, s41, 0
	s_nop 7
	v_add_f32_e32 v0, v0, v8
	v_add_f32_e32 v1, v1, v9
	v_add_f32_e32 v2, v2, v10
	v_add_f32_e32 v3, v3, v11
	v_add_f32_e32 v4, v4, v12
	v_add_f32_e32 v5, v5, v13
	v_add_f32_e32 v6, v6, v14
	v_add_f32_e32 v7, v7, v15
	v_mul_f32_e32 v0, v0, v224
	v_mul_f32_e32 v1, v1, v225
	v_mul_f32_e32 v2, v2, v226
	v_mul_f32_e32 v3, v3, v227
	v_mul_f32_e32 v4, v4, v228
	v_mul_f32_e32 v5, v5, v229
	v_mul_f32_e32 v6, v6, v230
	v_mul_f32_e32 v7, v7, v231
	s_barrier
	v_add_u32_e32 v236, s30, v248
	s_add_i32 m0, s42, 0x0
	s_add_u32 s30, s30, s37
	global_load_lds_dwordx4 v236, s[34:35]
	v_add_u32_e32 v236, s31, v248
	s_add_i32 m0, s43, 0x0
	s_add_u32 s31, s31, s38
	global_load_lds_dwordx4 v236, s[34:35]
	v_add_u32_e32 v236, s36, v248
	s_add_i32 m0, s61, 0x0
	s_add_u32 s36, s36, s39
	global_load_lds_dwordx4 v236, s[34:35]
	ds_read_b128 v[200:203], v248 offset:24576
	ds_read_b128 v[204:207], v248 offset:25600
	ds_read_b128 v[208:211], v249 offset:40960
	ds_read_b128 v[212:215], v249 offset:41024
	global_load_dwordx4 v[64:67], v248, s[28:29]
	global_load_dwordx4 v[68:71], v248, s[28:29] offset:1024
	global_load_dwordx4 v[72:75], v248, s[28:29] offset:2048
	global_load_dwordx4 v[76:79], v248, s[28:29] offset:3072
	s_add_u32 s28, s28, 0x20000
	s_addc_u32 s29, s29, 0
	ds_read_b128 v[216:219], v248 offset:26624
	ds_read_b128 v[220:223], v248 offset:27648
	ds_read_b128 v[224:227], v249 offset:41984
	ds_read_b128 v[228:231], v249 offset:42048
	s_waitcnt vmcnt(21)
	s_waitcnt lgkmcnt(4)
	v_mfma_f32_16x16x32_bf16 v[8:11], v[16:19], v[200:203], 0
	v_mfma_f32_16x16x32_bf16 v[12:15], v[24:27], v[200:203], 0
	v_mfma_f32_16x16x32_bf16 v[8:11], v[20:23], v[204:207], v[8:11]
	v_mfma_f32_16x16x32_bf16 v[12:15], v[28:31], v[204:207], v[12:15]
	v_cvt_pk_bf16_f32 v232, v0, v1
	v_cvt_pk_bf16_f32 v233, v2, v3
	v_cvt_pk_bf16_f32 v234, v4, v5
	v_cvt_pk_bf16_f32 v235, v6, v7
	global_store_dwordx2 v251, v[232:233], s[40:41]
	global_store_dwordx2 v251, v[234:235], s[40:41] offset:512
	s_add_u32 s40, s40, 0x100000
	s_addc_u32 s41, s41, 0
	s_nop 7
	v_add_f32_e32 v0, v0, v8
	v_add_f32_e32 v1, v1, v9
	v_add_f32_e32 v2, v2, v10
	v_add_f32_e32 v3, v3, v11
	v_add_f32_e32 v4, v4, v12
	v_add_f32_e32 v5, v5, v13
	v_add_f32_e32 v6, v6, v14
	v_add_f32_e32 v7, v7, v15
	v_mul_f32_e32 v0, v0, v208
	v_mul_f32_e32 v1, v1, v209
	v_mul_f32_e32 v2, v2, v210
	v_mul_f32_e32 v3, v3, v211
	v_mul_f32_e32 v4, v4, v212
	v_mul_f32_e32 v5, v5, v213
	v_mul_f32_e32 v6, v6, v214
	v_mul_f32_e32 v7, v7, v215
	global_load_dwordx4 v[16:19], v248, s[28:29]
	global_load_dwordx4 v[20:23], v248, s[28:29] offset:1024
	global_load_dwordx4 v[24:27], v248, s[28:29] offset:2048
	global_load_dwordx4 v[28:31], v248, s[28:29] offset:3072
	s_add_u32 s28, s28, 0x20000
	s_addc_u32 s29, s29, 0
	ds_read_b128 v[200:203], v248 offset:28672
	ds_read_b128 v[204:207], v248 offset:29696
	ds_read_b128 v[208:211], v249 offset:43008
	ds_read_b128 v[212:215], v249 offset:43072
	s_waitcnt vmcnt(21)
	s_waitcnt lgkmcnt(4)
	v_mfma_f32_16x16x32_bf16 v[8:11], v[32:35], v[216:219], 0
	v_mfma_f32_16x16x32_bf16 v[12:15], v[40:43], v[216:219], 0
	v_mfma_f32_16x16x32_bf16 v[8:11], v[36:39], v[220:223], v[8:11]
	v_mfma_f32_16x16x32_bf16 v[12:15], v[44:47], v[220:223], v[12:15]
	v_cvt_pk_bf16_f32 v232, v0, v1
	v_cvt_pk_bf16_f32 v233, v2, v3
	v_cvt_pk_bf16_f32 v234, v4, v5
	v_cvt_pk_bf16_f32 v235, v6, v7
	global_store_dwordx2 v251, v[232:233], s[40:41]
	global_store_dwordx2 v251, v[234:235], s[40:41] offset:512
	s_add_u32 s40, s40, 0x100000
	s_addc_u32 s41, s41, 0
	s_nop 7
	v_add_f32_e32 v0, v0, v8
	v_add_f32_e32 v1, v1, v9
	v_add_f32_e32 v2, v2, v10
	v_add_f32_e32 v3, v3, v11
	v_add_f32_e32 v4, v4, v12
	v_add_f32_e32 v5, v5, v13
	v_add_f32_e32 v6, v6, v14
	v_add_f32_e32 v7, v7, v15
	v_mul_f32_e32 v0, v0, v224
	v_mul_f32_e32 v1, v1, v225
	v_mul_f32_e32 v2, v2, v226
	v_mul_f32_e32 v3, v3, v227
	v_mul_f32_e32 v4, v4, v228
	v_mul_f32_e32 v5, v5, v229
	v_mul_f32_e32 v6, v6, v230
	v_mul_f32_e32 v7, v7, v231
	global_load_dwordx4 v[32:35], v248, s[28:29]
	global_load_dwordx4 v[36:39], v248, s[28:29] offset:1024
	global_load_dwordx4 v[40:43], v248, s[28:29] offset:2048
	global_load_dwordx4 v[44:47], v248, s[28:29] offset:3072
	s_add_u32 s28, s28, 0x20000
	s_addc_u32 s29, s29, 0
	ds_read_b128 v[216:219], v248 offset:30720
	ds_read_b128 v[220:223], v248 offset:31744
	ds_read_b128 v[224:227], v249 offset:44032
	ds_read_b128 v[228:231], v249 offset:44096
	s_waitcnt vmcnt(21)
; __device__ __forceinline__ unsigned pk2(float lo, float hi) { return pg8::cvt_pk_bf16(lo, hi); }
; template <int NDV>
; __device__ __forceinline__ void ph_g12_strip(Frame& F, int id) {
;     ...
;     for (int c0 = 0; c0 < 128; c0 += 4) {
; #pragma unroll
;         for (int u = 0; u < 4; ++u) {
;             const int cc = c0 + u;
;             unsigned char* slot = (unsigned char*)slot_ptr(F, ci0 + cc, h);
;             f32x4 D[2][NDV];
; #pragma unroll
;             for (int j = 0; j < 2; ++j)
; #pragma unroll
;                 for (int n = 0; n < NDV; ++n) { D[j][n] = (f32x4){0.f, 0.f, 0.f, 0.f};
; #pragma unroll
;                     for (int ks = 0; ks < 2; ++ks) D[j][n] = __builtin_amdgcn_mfma_f32_16x16x32_bf16(rk[u][j][ks], rv[u][n][ks], D[j][n], 0, 0, 0); }
; #pragma unroll
;             for (int j = 0; j < 2; ++j) { const int t = 2 * w + j, qd = t >> 2, c = t & 3; const f32x4 A = rA[u][j];
; #pragma unroll
;                 for (int n = 0; n < NDV; ++n) { const int nn = NDV * sl + n; v2u o; o.x = pk2(S[j][n][0], S[j][n][1]); o.y = pk2(S[j][n][2], S[j][n][3]);
;                     *(v2u*)(slot + (size_t)((nn * 8 + 2 * qd + (c >> 1)) * 64 + 2 * (c & 1) * 16) * 16 + sto) = o;
;                     S[j][n] = (S[j][n] + D[j][n]) * A; } }
;             if (cc + 4 < 128) G12_LOAD(u, cc + 4);
;         }
;     }
;     ...
; #pragma unroll
;     for (int j = 0; j < 2; ++j)
; #pragma unroll
;         for (int n = 0; n < NDV; ++n) { float* op = F.out + O_SGP + ((size_t)((seq * NH + h) * DK + 16 * (2 * w + j) + 4 * fq)) * DV + 16 * (NDV * sl + n) + fr;
; #pragma unroll
;             for (int i = 0; i < 4; ++i) op[(size_t)i * DV] = S[j][n][i]; }
	s_waitcnt lgkmcnt(4)
	v_mfma_f32_16x16x32_bf16 v[8:11], v[48:51], v[200:203], 0
	v_mfma_f32_16x16x32_bf16 v[12:15], v[56:59], v[200:203], 0
	v_mfma_f32_16x16x32_bf16 v[8:11], v[52:55], v[204:207], v[8:11]
	v_mfma_f32_16x16x32_bf16 v[12:15], v[60:63], v[204:207], v[12:15]
	v_cvt_pk_bf16_f32 v232, v0, v1
	v_cvt_pk_bf16_f32 v233, v2, v3
	v_cvt_pk_bf16_f32 v234, v4, v5
	v_cvt_pk_bf16_f32 v235, v6, v7
	global_store_dwordx2 v251, v[232:233], s[40:41]
	global_store_dwordx2 v251, v[234:235], s[40:41] offset:512
	s_add_u32 s40, s40, 0x100000
	s_addc_u32 s41, s41, 0
	s_nop 7
	v_add_f32_e32 v0, v0, v8
	v_add_f32_e32 v1, v1, v9
	v_add_f32_e32 v2, v2, v10
	v_add_f32_e32 v3, v3, v11
	v_add_f32_e32 v4, v4, v12
	v_add_f32_e32 v5, v5, v13
	v_add_f32_e32 v6, v6, v14
	v_add_f32_e32 v7, v7, v15
	v_mul_f32_e32 v0, v0, v208
	v_mul_f32_e32 v1, v1, v209
	v_mul_f32_e32 v2, v2, v210
	v_mul_f32_e32 v3, v3, v211
	v_mul_f32_e32 v4, v4, v212
	v_mul_f32_e32 v5, v5, v213
	v_mul_f32_e32 v6, v6, v214
	v_mul_f32_e32 v7, v7, v215
	global_load_dwordx4 v[48:51], v248, s[28:29]
	global_load_dwordx4 v[52:55], v248, s[28:29] offset:1024
	global_load_dwordx4 v[56:59], v248, s[28:29] offset:2048
	global_load_dwordx4 v[60:63], v248, s[28:29] offset:3072
	s_add_u32 s28, s28, 0x20000
	s_addc_u32 s29, s29, 0
	ds_read_b128 v[200:203], v248 offset:32768
	ds_read_b128 v[204:207], v248 offset:33792
	ds_read_b128 v[208:211], v249 offset:45056
	ds_read_b128 v[212:215], v249 offset:45120
	s_waitcnt vmcnt(18)
	s_waitcnt lgkmcnt(4)
	v_mfma_f32_16x16x32_bf16 v[8:11], v[64:67], v[216:219], 0
	v_mfma_f32_16x16x32_bf16 v[12:15], v[72:75], v[216:219], 0
	v_mfma_f32_16x16x32_bf16 v[8:11], v[68:71], v[220:223], v[8:11]
	v_mfma_f32_16x16x32_bf16 v[12:15], v[76:79], v[220:223], v[12:15]
	v_cvt_pk_bf16_f32 v232, v0, v1
	v_cvt_pk_bf16_f32 v233, v2, v3
	v_cvt_pk_bf16_f32 v234, v4, v5
	v_cvt_pk_bf16_f32 v235, v6, v7
	global_store_dwordx2 v251, v[232:233], s[40:41]
	global_store_dwordx2 v251, v[234:235], s[40:41] offset:512
	s_add_u32 s40, s40, 0x100000
	s_addc_u32 s41, s41, 0
	s_nop 7
	v_add_f32_e32 v0, v0, v8
	v_add_f32_e32 v1, v1, v9
	v_add_f32_e32 v2, v2, v10
	v_add_f32_e32 v3, v3, v11
	v_add_f32_e32 v4, v4, v12
	v_add_f32_e32 v5, v5, v13
	v_add_f32_e32 v6, v6, v14
	v_add_f32_e32 v7, v7, v15
	v_mul_f32_e32 v0, v0, v224
	v_mul_f32_e32 v1, v1, v225
	v_mul_f32_e32 v2, v2, v226
	v_mul_f32_e32 v3, v3, v227
	v_mul_f32_e32 v4, v4, v228
	v_mul_f32_e32 v5, v5, v229
	v_mul_f32_e32 v6, v6, v230
	v_mul_f32_e32 v7, v7, v231
	global_load_dwordx4 v[64:67], v248, s[28:29]
	global_load_dwordx4 v[68:71], v248, s[28:29] offset:1024
	global_load_dwordx4 v[72:75], v248, s[28:29] offset:2048
	global_load_dwordx4 v[76:79], v248, s[28:29] offset:3072
	s_add_u32 s28, s28, 0x20000
	s_addc_u32 s29, s29, 0
	ds_read_b128 v[216:219], v248 offset:34816
	ds_read_b128 v[220:223], v248 offset:35840
	ds_read_b128 v[224:227], v249 offset:46080
	ds_read_b128 v[228:231], v249 offset:46144
	s_waitcnt vmcnt(18)
	s_waitcnt lgkmcnt(4)
	v_mfma_f32_16x16x32_bf16 v[8:11], v[16:19], v[200:203], 0
	v_mfma_f32_16x16x32_bf16 v[12:15], v[24:27], v[200:203], 0
	v_mfma_f32_16x16x32_bf16 v[8:11], v[20:23], v[204:207], v[8:11]
	v_mfma_f32_16x16x32_bf16 v[12:15], v[28:31], v[204:207], v[12:15]
	v_cvt_pk_bf16_f32 v232, v0, v1
	v_cvt_pk_bf16_f32 v233, v2, v3
	v_cvt_pk_bf16_f32 v234, v4, v5
	v_cvt_pk_bf16_f32 v235, v6, v7
	global_store_dwordx2 v251, v[232:233], s[40:41]
	global_store_dwordx2 v251, v[234:235], s[40:41] offset:512
	s_add_u32 s40, s40, 0x100000
	s_addc_u32 s41, s41, 0
	s_nop 7
	v_add_f32_e32 v0, v0, v8
	v_add_f32_e32 v1, v1, v9
	v_add_f32_e32 v2, v2, v10
	v_add_f32_e32 v3, v3, v11
	v_add_f32_e32 v4, v4, v12
	v_add_f32_e32 v5, v5, v13
	v_add_f32_e32 v6, v6, v14
	v_add_f32_e32 v7, v7, v15
	v_mul_f32_e32 v0, v0, v208
	v_mul_f32_e32 v1, v1, v209
	v_mul_f32_e32 v2, v2, v210
	v_mul_f32_e32 v3, v3, v211
	v_mul_f32_e32 v4, v4, v212
	v_mul_f32_e32 v5, v5, v213
	v_mul_f32_e32 v6, v6, v214
	v_mul_f32_e32 v7, v7, v215
	global_load_dwordx4 v[16:19], v248, s[28:29]
	global_load_dwordx4 v[20:23], v248, s[28:29] offset:1024
	global_load_dwordx4 v[24:27], v248, s[28:29] offset:2048
	global_load_dwordx4 v[28:31], v248, s[28:29] offset:3072
	s_add_u32 s28, s28, 0x20000
	s_addc_u32 s29, s29, 0
	ds_read_b128 v[200:203], v248 offset:36864
	ds_read_b128 v[204:207], v248 offset:37888
	ds_read_b128 v[208:211], v249 offset:47104
	ds_read_b128 v[212:215], v249 offset:47168
	s_waitcnt vmcnt(18)
	s_waitcnt lgkmcnt(4)
; __device__ __forceinline__ unsigned pk2(float lo, float hi) { return pg8::cvt_pk_bf16(lo, hi); }
; template <int NDV>
; __device__ __forceinline__ void ph_g12_strip(Frame& F, int id) {
;     ...
;     for (int c0 = 0; c0 < 128; c0 += 4) {
; #pragma unroll
;         for (int u = 0; u < 4; ++u) {
;             const int cc = c0 + u;
;             unsigned char* slot = (unsigned char*)slot_ptr(F, ci0 + cc, h);
;             f32x4 D[2][NDV];
; #pragma unroll
;             for (int j = 0; j < 2; ++j)
; #pragma unroll
;                 for (int n = 0; n < NDV; ++n) { D[j][n] = (f32x4){0.f, 0.f, 0.f, 0.f};
; #pragma unroll
;                     for (int ks = 0; ks < 2; ++ks) D[j][n] = __builtin_amdgcn_mfma_f32_16x16x32_bf16(rk[u][j][ks], rv[u][n][ks], D[j][n], 0, 0, 0); }
; #pragma unroll
;             for (int j = 0; j < 2; ++j) { const int t = 2 * w + j, qd = t >> 2, c = t & 3; const f32x4 A = rA[u][j];
; #pragma unroll
;                 for (int n = 0; n < NDV; ++n) { const int nn = NDV * sl + n; v2u o; o.x = pk2(S[j][n][0], S[j][n][1]); o.y = pk2(S[j][n][2], S[j][n][3]);
;                     *(v2u*)(slot + (size_t)((nn * 8 + 2 * qd + (c >> 1)) * 64 + 2 * (c & 1) * 16) * 16 + sto) = o;
;                     S[j][n] = (S[j][n] + D[j][n]) * A; } }
;             if (cc + 4 < 128) G12_LOAD(u, cc + 4);
;         }
;     }
;     ...
; #pragma unroll
;     for (int j = 0; j < 2; ++j)
; #pragma unroll
;         for (int n = 0; n < NDV; ++n) { float* op = F.out + O_SGP + ((size_t)((seq * NH + h) * DK + 16 * (2 * w + j) + 4 * fq)) * DV + 16 * (NDV * sl + n) + fr;
; #pragma unroll
;             for (int i = 0; i < 4; ++i) op[(size_t)i * DV] = S[j][n][i]; }
	v_mfma_f32_16x16x32_bf16 v[8:11], v[32:35], v[216:219], 0
	v_mfma_f32_16x16x32_bf16 v[12:15], v[40:43], v[216:219], 0
	v_mfma_f32_16x16x32_bf16 v[8:11], v[36:39], v[220:223], v[8:11]
	v_mfma_f32_16x16x32_bf16 v[12:15], v[44:47], v[220:223], v[12:15]
	v_cvt_pk_bf16_f32 v232, v0, v1
	v_cvt_pk_bf16_f32 v233, v2, v3
	v_cvt_pk_bf16_f32 v234, v4, v5
	v_cvt_pk_bf16_f32 v235, v6, v7
	global_store_dwordx2 v251, v[232:233], s[40:41]
	global_store_dwordx2 v251, v[234:235], s[40:41] offset:512
	s_add_u32 s40, s40, 0x100000
	s_addc_u32 s41, s41, 0
	s_nop 7
	v_add_f32_e32 v0, v0, v8
	v_add_f32_e32 v1, v1, v9
	v_add_f32_e32 v2, v2, v10
	v_add_f32_e32 v3, v3, v11
	v_add_f32_e32 v4, v4, v12
	v_add_f32_e32 v5, v5, v13
	v_add_f32_e32 v6, v6, v14
	v_add_f32_e32 v7, v7, v15
	v_mul_f32_e32 v0, v0, v224
	v_mul_f32_e32 v1, v1, v225
	v_mul_f32_e32 v2, v2, v226
	v_mul_f32_e32 v3, v3, v227
	v_mul_f32_e32 v4, v4, v228
	v_mul_f32_e32 v5, v5, v229
	v_mul_f32_e32 v6, v6, v230
	v_mul_f32_e32 v7, v7, v231
	global_load_dwordx4 v[32:35], v248, s[28:29]
	global_load_dwordx4 v[36:39], v248, s[28:29] offset:1024
	global_load_dwordx4 v[40:43], v248, s[28:29] offset:2048
	global_load_dwordx4 v[44:47], v248, s[28:29] offset:3072
	s_add_u32 s28, s28, 0x20000
	s_addc_u32 s29, s29, 0
	ds_read_b128 v[216:219], v248 offset:38912
	ds_read_b128 v[220:223], v248 offset:39936
	ds_read_b128 v[224:227], v249 offset:48128
	ds_read_b128 v[228:231], v249 offset:48192
	s_waitcnt vmcnt(18)
	s_waitcnt lgkmcnt(4)
	v_mfma_f32_16x16x32_bf16 v[8:11], v[48:51], v[200:203], 0
	v_mfma_f32_16x16x32_bf16 v[12:15], v[56:59], v[200:203], 0
	v_mfma_f32_16x16x32_bf16 v[8:11], v[52:55], v[204:207], v[8:11]
	v_mfma_f32_16x16x32_bf16 v[12:15], v[60:63], v[204:207], v[12:15]
	v_cvt_pk_bf16_f32 v232, v0, v1
	v_cvt_pk_bf16_f32 v233, v2, v3
	v_cvt_pk_bf16_f32 v234, v4, v5
	v_cvt_pk_bf16_f32 v235, v6, v7
	global_store_dwordx2 v251, v[232:233], s[40:41]
	global_store_dwordx2 v251, v[234:235], s[40:41] offset:512
	s_add_u32 s40, s40, 0x100000
	s_addc_u32 s41, s41, 0
	s_nop 7
	v_add_f32_e32 v0, v0, v8
	v_add_f32_e32 v1, v1, v9
	v_add_f32_e32 v2, v2, v10
	v_add_f32_e32 v3, v3, v11
	v_add_f32_e32 v4, v4, v12
	v_add_f32_e32 v5, v5, v13
	v_add_f32_e32 v6, v6, v14
	v_add_f32_e32 v7, v7, v15
	v_mul_f32_e32 v0, v0, v208
	v_mul_f32_e32 v1, v1, v209
	v_mul_f32_e32 v2, v2, v210
	v_mul_f32_e32 v3, v3, v211
	v_mul_f32_e32 v4, v4, v212
	v_mul_f32_e32 v5, v5, v213
	v_mul_f32_e32 v6, v6, v214
	v_mul_f32_e32 v7, v7, v215
	global_load_dwordx4 v[48:51], v248, s[28:29]
	global_load_dwordx4 v[52:55], v248, s[28:29] offset:1024
	global_load_dwordx4 v[56:59], v248, s[28:29] offset:2048
	global_load_dwordx4 v[60:63], v248, s[28:29] offset:3072
	s_add_u32 s28, s28, 0x20000
	s_addc_u32 s29, s29, 0
	s_waitcnt vmcnt(18)
	s_waitcnt lgkmcnt(0)
	v_mfma_f32_16x16x32_bf16 v[8:11], v[64:67], v[216:219], 0
	v_mfma_f32_16x16x32_bf16 v[12:15], v[72:75], v[216:219], 0
	v_mfma_f32_16x16x32_bf16 v[8:11], v[68:71], v[220:223], v[8:11]
	v_mfma_f32_16x16x32_bf16 v[12:15], v[76:79], v[220:223], v[12:15]
	v_cvt_pk_bf16_f32 v232, v0, v1
	v_cvt_pk_bf16_f32 v233, v2, v3
	v_cvt_pk_bf16_f32 v234, v4, v5
	v_cvt_pk_bf16_f32 v235, v6, v7
	global_store_dwordx2 v251, v[232:233], s[40:41]
	global_store_dwordx2 v251, v[234:235], s[40:41] offset:512
	s_add_u32 s40, s40, 0x100000
	s_addc_u32 s41, s41, 0
	s_nop 7
	v_add_f32_e32 v0, v0, v8
	v_add_f32_e32 v1, v1, v9
	v_add_f32_e32 v2, v2, v10
	v_add_f32_e32 v3, v3, v11
	v_add_f32_e32 v4, v4, v12
	v_add_f32_e32 v5, v5, v13
	v_add_f32_e32 v6, v6, v14
	v_add_f32_e32 v7, v7, v15
	v_mul_f32_e32 v0, v0, v224
	v_mul_f32_e32 v1, v1, v225
	v_mul_f32_e32 v2, v2, v226
	v_mul_f32_e32 v3, v3, v227
	v_mul_f32_e32 v4, v4, v228
	v_mul_f32_e32 v5, v5, v229
	v_mul_f32_e32 v6, v6, v230
	v_mul_f32_e32 v7, v7, v231
	s_sub_i32 s8, s8, 1
	s_cmp_lg_u32 s8, 0
	s_cbranch_scc1 .Lstrip2_loop
	s_waitcnt vmcnt(0) lgkmcnt(0)
	s_barrier
	s_lshl_b32 s0, s58, 2
	s_add_u32 s0, s0, s59
	s_lshl_b32 s0, s0, 19
	s_lshl_b32 s1, s79, 16
	s_add_u32 s0, s0, s1
	s_lshl_b32 s1, s60, 6
	s_add_u32 s0, s0, s1
	s_add_u32 s0, s0, 0x12000000
	s_add_u32 s0, s70, s0
	s_addc_u32 s1, s71, 0
	v_and_b32_e32 v236, 15, v166
	v_lshrrev_b32_e32 v237, 4, v166
	v_lshlrev_b32_e32 v236, 2, v236
	v_lshl_add_u32 v236, v237, 13, v236
	v_add_u32_e32 v237, 0x1000, v236
	global_store_dword v236, v0, s[0:1]
	global_store_dword v236, v1, s[0:1] offset:2048
	global_store_dword v237, v2, s[0:1]
	global_store_dword v237, v3, s[0:1] offset:2048
	s_add_u32 s0, s0, 0x8000
	s_addc_u32 s1, s1, 0
	global_store_dword v236, v4, s[0:1]
	global_store_dword v236, v5, s[0:1] offset:2048
	global_store_dword v237, v6, s[0:1]
	global_store_dword v237, v7, s[0:1] offset:2048
	s_branch .LBB0_474

;     __host__ __device__ bool next(int i, Unit& u) const {
;     ...
;                 int wgid = (int)L; { const int qq = nwg / NXCD, r = nwg % NXCD, xcd = wgid % NXCD, off = wgid / NXCD; wgid = (xcd < r ? xcd * (qq + 1) : r * (qq + 1) + (xcd - r) * qq) + off; }
;                 const int nig = WGM * nN, gid = wgid / nig, fm = gid * WGM, gsz = (nM - fm) < WGM ? (nM - fm) : WGM;
;                 u.pm = fm + ((wgid % nig) % gsz); u.pn = (wgid % nig) / gsz; u.prob = q;
;                 u.a = p[q].A + (size_t)u.pm * tstep; u.b = p[q].B + (size_t)u.pn * tstep; u.pm += p[q].pm0; u.pn += p[q].pn0; u.nt = p[q].nt; u.f8 = p[q].f8; return true; }
.LBB0_745:
	s_ashr_i32 s8, s8, 3
	s_add_i32 s8, s23, s8
	s_ashr_i32 s9, s8, 31
	s_lshr_b32 s9, s9, 25
	s_add_i32 s9, s8, s9
	s_ashr_i32 s23, s9, 7
	s_lshl_b32 s23, s23, 3
	s_sub_i32 s24, 64, s23
	s_min_i32 s25, s24, 8
	s_abs_i32 s24, s25
	v_cvt_f32_u32_e32 v1, s24
	s_sub_i32 s27, 0, s24
	s_andn2_b32 s9, s9, 127
	s_sub_i32 s8, s8, s9
	v_rcp_iflag_f32_e32 v1, v1
	s_abs_i32 s9, s8
	s_xor_b32 s26, s8, s25
	s_ashr_i32 s26, s26, 31
	v_mul_f32_e32 v1, 0x4f7ffffe, v1
	v_cvt_u32_f32_e32 v1, v1
	s_mov_b32 s46, 64
	s_mov_b32 s45, 0
	s_mov_b64 s[36:37], s[38:39]
	v_readfirstlane_b32 s28, v1
	s_mul_i32 s27, s27, s28
	s_mul_hi_u32 s27, s28, s27
	s_add_i32 s28, s28, s27
	s_mul_hi_u32 s27, s9, s28
	s_mul_i32 s28, s27, s24
	s_sub_i32 s9, s9, s28
	s_add_i32 s29, s27, 1
	s_sub_i32 s28, s9, s24
	s_cmp_ge_u32 s9, s24
	s_cselect_b32 s27, s29, s27
	s_cselect_b32 s9, s28, s9
	s_add_i32 s28, s27, 1
	s_cmp_ge_u32 s9, s24
	s_cselect_b32 s9, s28, s27
	s_xor_b32 s9, s9, s26
	s_sub_i32 s24, s9, s26
	s_mul_i32 s9, s24, s25
	s_sub_i32 s8, s8, s9
	s_add_i32 s30, s8, s23
	s_ashr_i32 s31, s30, 31
	s_lshl_b64 s[8:9], s[30:31], 21
	v_readlane_b32 s23, v255, 3
	s_add_u32 s26, s23, s8
	v_readlane_b32 s8, v255, 46
	s_addc_u32 s27, s8, s9
	s_ashr_i32 s25, s24, 31
	s_lshl_b64 s[8:9], s[24:25], 21
	s_add_u32 s28, s73, s8
	s_addc_u32 s29, s74, s9
	s_mov_b64 s[38:39], -1
	s_and_b64 vcc, exec, s[6:7]
	s_cbranch_vccz .LBB0_761

;     __host__ __device__ bool next(int i, Unit& u) const {
;     ...
;                 int wgid = (int)L; { const int qq = nwg / NXCD, r = nwg % NXCD, xcd = wgid % NXCD, off = wgid / NXCD; wgid = (xcd < r ? xcd * (qq + 1) : r * (qq + 1) + (xcd - r) * qq) + off; }
;                 const int nig = WGM * nN, gid = wgid / nig, fm = gid * WGM, gsz = (nM - fm) < WGM ? (nM - fm) : WGM;
;                 u.pm = fm + ((wgid % nig) % gsz); u.pn = (wgid % nig) / gsz; u.prob = q;
;                 u.a = p[q].A + (size_t)u.pm * tstep; u.b = p[q].B + (size_t)u.pn * tstep; u.pm += p[q].pm0; u.pn += p[q].pn0; u.nt = p[q].nt; u.f8 = p[q].f8; return true; }
.LBB0_754:
	s_ashr_i32 s8, s8, 3
	s_add_i32 s8, s23, s8
	s_ashr_i32 s9, s8, 31
	s_lshr_b32 s9, s9, 25
	s_add_i32 s9, s8, s9
	s_ashr_i32 s23, s9, 7
	s_lshl_b32 s23, s23, 3
	s_sub_i32 s24, 8, s23
	s_min_i32 s25, s24, 8
	s_abs_i32 s24, s25
	v_cvt_f32_u32_e32 v1, s24
	s_sub_i32 s27, 0, s24
	s_andn2_b32 s9, s9, 127
	s_sub_i32 s8, s8, s9
	v_rcp_iflag_f32_e32 v1, v1
	s_abs_i32 s9, s8
	s_xor_b32 s26, s8, s25
	s_ashr_i32 s26, s26, 31
	v_mul_f32_e32 v1, 0x4f7ffffe, v1
	v_cvt_u32_f32_e32 v1, v1
	s_mov_b32 s45, 1
	s_mov_b32 s46, 32
	s_mov_b64 s[40:41], s[36:37]
	v_readfirstlane_b32 s28, v1
	s_mul_i32 s27, s27, s28
	s_mul_hi_u32 s27, s28, s27
	s_add_i32 s28, s28, s27
	s_mul_hi_u32 s27, s9, s28
	s_mul_i32 s28, s27, s24
	s_sub_i32 s9, s9, s28
	s_add_i32 s29, s27, 1
	s_sub_i32 s28, s9, s24
	s_cmp_ge_u32 s9, s24
	s_cselect_b32 s27, s29, s27
	s_cselect_b32 s9, s28, s9
	s_add_i32 s28, s27, 1
	s_cmp_ge_u32 s9, s24
	s_cselect_b32 s9, s28, s27
	s_xor_b32 s9, s9, s26
	s_sub_i32 s24, s9, s26
	s_mul_i32 s9, s24, s25
	s_sub_i32 s8, s8, s9
	s_add_i32 s8, s8, s23
	s_ashr_i32 s9, s8, 31
	s_lshl_b64 s[26:27], s[8:9], 21
	v_readlane_b32 s9, v255, 48
	s_add_u32 s26, s9, s26
	v_readlane_b32 s9, v255, 44
	s_addc_u32 s27, s9, s27
	s_ashr_i32 s25, s24, 31
	s_lshl_b64 s[28:29], s[24:25], 21
	s_add_u32 s28, s73, s28
	s_addc_u32 s29, s74, s29
	s_add_i32 s30, s8, 64
	s_andn2_b64 vcc, exec, s[6:7]
	s_mov_b64 s[38:39], -1
	s_cbranch_vccnz .LBB0_761

;     __host__ __device__ bool next(int i, Unit& u) const {
;     ...
;                 int wgid = (int)L; { const int qq = nwg / NXCD, r = nwg % NXCD, xcd = wgid % NXCD, off = wgid / NXCD; wgid = (xcd < r ? xcd * (qq + 1) : r * (qq + 1) + (xcd - r) * qq) + off; }
;                 const int nig = WGM * nN, gid = wgid / nig, fm = gid * WGM, gsz = (nM - fm) < WGM ? (nM - fm) : WGM;
;                 u.pm = fm + ((wgid % nig) % gsz); u.pn = (wgid % nig) / gsz; u.prob = q;
;                 u.a = p[q].A + (size_t)u.pm * tstep; u.b = p[q].B + (size_t)u.pn * tstep; u.pm += p[q].pm0; u.pn += p[q].pn0; u.nt = p[q].nt; u.f8 = p[q].f8; return true; }
.LBB0_760:
	s_ashr_i32 s6, s8, 3
	s_add_i32 s6, s23, s6
	s_ashr_i32 s7, s6, 31
	s_lshr_b32 s7, s7, 25
	s_add_i32 s7, s6, s7
	s_ashr_i32 s8, s7, 7
	s_lshl_b32 s8, s8, 3
	s_sub_i32 s9, 8, s8
	s_min_i32 s9, s9, 8
	s_abs_i32 s23, s9
	v_cvt_f32_u32_e32 v1, s23
	s_sub_i32 s25, 0, s23
	s_andn2_b32 s7, s7, 127
	s_sub_i32 s6, s6, s7
	v_rcp_iflag_f32_e32 v1, v1
	s_abs_i32 s7, s6
	s_xor_b32 s24, s6, s9
	s_ashr_i32 s24, s24, 31
	v_mul_f32_e32 v1, 0x4f7ffffe, v1
	v_cvt_u32_f32_e32 v1, v1
	s_mov_b32 s45, 2
	s_mov_b32 s46, 32
	s_mov_b64 s[38:39], -1
	v_readfirstlane_b32 s26, v1
	s_mul_i32 s25, s25, s26
	s_mul_hi_u32 s25, s26, s25
	s_add_i32 s26, s26, s25
	s_mul_hi_u32 s25, s7, s26
	s_mul_i32 s26, s25, s23
	s_sub_i32 s7, s7, s26
	s_add_i32 s27, s25, 1
	s_sub_i32 s26, s7, s23
	s_cmp_ge_u32 s7, s23
	s_cselect_b32 s25, s27, s25
	s_cselect_b32 s7, s26, s7
	s_add_i32 s26, s25, 1
	s_cmp_ge_u32 s7, s23
	s_cselect_b32 s7, s26, s25
	s_xor_b32 s7, s7, s24
	s_sub_i32 s24, s7, s24
	s_mul_i32 s7, s24, s9
	s_sub_i32 s6, s6, s7
	s_add_i32 s6, s6, s8
	s_ashr_i32 s7, s6, 31
	s_lshl_b64 s[8:9], s[6:7], 21
	v_readlane_b32 s7, v255, 50
	s_add_u32 s26, s7, s8
	v_readlane_b32 s7, v255, 51
	s_addc_u32 s27, s7, s9
	s_ashr_i32 s25, s24, 31
	s_lshl_b64 s[8:9], s[24:25], 21
	v_readlane_b32 s7, v255, 52
	s_add_u32 s28, s7, s8
	v_readlane_b32 s7, v255, 53
	s_addc_u32 s29, s7, s9
	s_add_i32 s30, s6, 64

; #define PG8_STAGE(bufoff, gbase, voff) do { _Pragma("unroll") for (int _i = 0; _i < 2; ++_i) \
;         __builtin_amdgcn_global_load_lds((const unsigned*)((const char*)(gbase) + (voff)[_i]), (PG8_LAS unsigned*)(lds + (bufoff) + ldsw + _i * 8192), 16, 0, 0); } while (0)
; #define PG8_LDA(dst, b, h) do { _Pragma("unroll") for (int m = 0; m < 4; ++m) _Pragma("unroll") for (int k = 0; k < 2; ++k) dst[m][k] = *(const PG8_LAS bf16x8*)(lds + PG8_SA(b, h) + aoff + m * 2048 + k * 1024); } while (0)
; #define PG8_LDB(dst, b, h) do { _Pragma("unroll") for (int n = 0; n < 2; ++n) _Pragma("unroll") for (int k = 0; k < 2; ++k) dst[n][k] = *(const PG8_LAS bf16x8*)(lds + PG8_SB(b, h) + boff + n * 2048 + k * 1024); } while (0)
; #define PG8_WAIT_V(n) asm volatile("s_waitcnt vmcnt(" #n ")" ::: "memory")
; #define PG8_WAIT_L(n) asm volatile("s_waitcnt lgkmcnt(" #n ")" ::: "memory")
; #define PG8_BAR __builtin_amdgcn_s_barrier()
; #define PG8_SCHED __builtin_amdgcn_sched_barrier(0)
; template <class Epi, class Sched, bool ALIGN_EPI = false, bool SP2 = false, bool F8 = false>
; __device__ __forceinline__ void gemm_phase(PG8_LAS unsigned char* lds, const int K, const Sched& S, const Epi& E, const int wave) {
;     ...
;             PG8_LDB(B0, 0, 0); PG8_LDB(B1, 0, 1); PG8_SCHED; PG8_LDA(At, 0, 0); PG8_STAGE(PG8_SA(1, 1), a1 + hstep, voffA);
;             PG8_WAIT_V(8); PG8_WAIT_L(0); PG8_BAR; PG8_MMA(0, 0, At, B0); PG8_MMA(0, 1, At, B1); PG8_BAR; PG8_SCHED;
;             PG8_LDA(At, 0, 1); PG8_STAGE(PG8_SB(0, 0), b2, voffB); PG8_STAGE(PG8_SB(0, 1), b2 + hstep, voffB); PG8_STAGE(PG8_SA(0, 0), a2, voffA);
;             PG8_WAIT_V(8); PG8_WAIT_L(0); PG8_BAR; PG8_MMA(1, 0, At, B0); PG8_MMA(1, 1, At, B1); PG8_BAR; PG8_SCHED;
.LBB0_763:
	v_add_u32_e32 v1, s82, v220
	ds_read_b128 v[132:135], v1
	ds_read_b128 v[136:139], v1 offset:1024
	ds_read_b128 v[140:143], v1 offset:2048
	ds_read_b128 v[144:147], v1 offset:3072
	v_add_u32_e32 v1, s75, v220
	ds_read_b128 v[148:151], v1
	ds_read_b128 v[152:155], v1 offset:1024
	ds_read_b128 v[156:159], v1 offset:2048
	ds_read_b128 v[160:163], v1 offset:3072
	s_add_i32 s9, s9, 2
	s_add_u32 s64, s64, 0x100000
	s_addc_u32 s65, s65, 0
	s_add_i32 m0, s87, 0xc000
	ds_read_b128 v[182:185], v222
	ds_read_b128 v[186:189], v222 offset:1024
	ds_read_b128 v[190:193], v222 offset:2048
	ds_read_b128 v[194:197], v222 offset:3072
	ds_read_b128 v[198:201], v222 offset:4096
	ds_read_b128 v[202:205], v222 offset:5120
	ds_read_b128 v[206:209], v222 offset:6144
	ds_read_b128 v[210:213], v222 offset:7168
	global_load_lds_dwordx4 v164, s[64:65]
	s_add_i32 m0, s87, 0xe000
	s_nop 0
	global_load_lds_dwordx4 v168, s[64:65]
	s_waitcnt vmcnt(8)
	s_waitcnt lgkmcnt(0)
	s_setprio 1
	s_barrier
	v_mfma_f32_16x16x32_bf16 v[128:131], v[132:135], v[182:185], v[128:131]
	v_mfma_f32_16x16x32_bf16 v[124:127], v[140:143], v[182:185], v[124:127]
	v_mfma_f32_16x16x32_bf16 v[120:123], v[132:135], v[190:193], v[120:123]
	v_mfma_f32_16x16x32_bf16 v[116:119], v[140:143], v[190:193], v[116:119]
	v_mfma_f32_16x16x32_bf16 v[112:115], v[132:135], v[198:201], v[112:115]
	v_mfma_f32_16x16x32_bf16 v[108:111], v[140:143], v[198:201], v[108:111]
	v_mfma_f32_16x16x32_bf16 v[104:107], v[132:135], v[206:209], v[104:107]
	v_mfma_f32_16x16x32_bf16 v[100:103], v[140:143], v[206:209], v[100:103]
	v_mfma_f32_16x16x32_bf16 v[128:131], v[136:139], v[186:189], v[128:131]
	v_mfma_f32_16x16x32_bf16 v[124:127], v[144:147], v[186:189], v[124:127]
	v_mfma_f32_16x16x32_bf16 v[120:123], v[136:139], v[194:197], v[120:123]
	v_mfma_f32_16x16x32_bf16 v[116:119], v[144:147], v[194:197], v[116:119]
	v_mfma_f32_16x16x32_bf16 v[112:115], v[136:139], v[202:205], v[112:115]
	v_mfma_f32_16x16x32_bf16 v[108:111], v[144:147], v[202:205], v[108:111]
	v_mfma_f32_16x16x32_bf16 v[104:107], v[136:139], v[210:213], v[104:107]
	v_mfma_f32_16x16x32_bf16 v[100:103], v[144:147], v[210:213], v[100:103]
	v_mfma_f32_16x16x32_bf16 v[96:99], v[148:151], v[182:185], v[96:99]
	v_mfma_f32_16x16x32_bf16 v[92:95], v[156:159], v[182:185], v[92:95]
	v_mfma_f32_16x16x32_bf16 v[88:91], v[148:151], v[190:193], v[88:91]
	v_mfma_f32_16x16x32_bf16 v[84:87], v[156:159], v[190:193], v[84:87]
	v_mfma_f32_16x16x32_bf16 v[80:83], v[148:151], v[198:201], v[80:83]
	v_mfma_f32_16x16x32_bf16 v[76:79], v[156:159], v[198:201], v[76:79]
	v_mfma_f32_16x16x32_bf16 v[72:75], v[148:151], v[206:209], v[72:75]
	v_mfma_f32_16x16x32_bf16 v[68:71], v[156:159], v[206:209], v[68:71]
	v_mfma_f32_16x16x32_bf16 v[96:99], v[152:155], v[186:189], v[96:99]
	v_mfma_f32_16x16x32_bf16 v[92:95], v[160:163], v[186:189], v[92:95]
	v_mfma_f32_16x16x32_bf16 v[88:91], v[152:155], v[194:197], v[88:91]
	v_mfma_f32_16x16x32_bf16 v[84:87], v[160:163], v[194:197], v[84:87]
	v_mfma_f32_16x16x32_bf16 v[80:83], v[152:155], v[202:205], v[80:83]
	v_mfma_f32_16x16x32_bf16 v[76:79], v[160:163], v[202:205], v[76:79]
	v_mfma_f32_16x16x32_bf16 v[72:75], v[152:155], v[210:213], v[72:75]
	v_mfma_f32_16x16x32_bf16 v[68:71], v[160:163], v[210:213], v[68:71]
	s_barrier
	s_setprio 0
	s_add_i32 s64, s82, s86
	s_mov_b32 m0, s64
	ds_read_b128 v[182:185], v222 offset:16384
	ds_read_b128 v[186:189], v222 offset:17408
	ds_read_b128 v[190:193], v222 offset:18432
	ds_read_b128 v[194:197], v222 offset:19456
	ds_read_b128 v[198:201], v222 offset:20480
	ds_read_b128 v[202:205], v222 offset:21504
	ds_read_b128 v[206:209], v222 offset:22528
	ds_read_b128 v[210:213], v222 offset:23552
	global_load_lds_dwordx4 v166, s[62:63]
	s_add_i32 m0, s64, 0x2000
	s_nop 0
	global_load_lds_dwordx4 v170, s[62:63]
	s_add_u32 s62, s62, 0x100000
	s_addc_u32 s63, s63, 0
	s_add_i32 s64, s75, s86
	s_mov_b32 m0, s64
	s_nop 0
	global_load_lds_dwordx4 v166, s[62:63]
	s_add_i32 m0, s64, 0x2000
	s_nop 0
	global_load_lds_dwordx4 v170, s[62:63]
	s_mov_b32 m0, s87
	s_nop 0
	global_load_lds_dwordx4 v164, s[60:61]
	s_mov_b32 m0, s88
	s_nop 0
	global_load_lds_dwordx4 v168, s[60:61]
	s_waitcnt vmcnt(8)
	s_waitcnt lgkmcnt(0)
	s_setprio 1
	s_barrier
	v_mfma_f32_16x16x32_bf16 v[64:67], v[132:135], v[182:185], v[64:67]
	v_mfma_f32_16x16x32_bf16 v[60:63], v[140:143], v[182:185], v[60:63]
	v_mfma_f32_16x16x32_bf16 v[56:59], v[132:135], v[190:193], v[56:59]
	v_mfma_f32_16x16x32_bf16 v[52:55], v[140:143], v[190:193], v[52:55]
	v_mfma_f32_16x16x32_bf16 v[48:51], v[132:135], v[198:201], v[48:51]
	v_mfma_f32_16x16x32_bf16 v[44:47], v[140:143], v[198:201], v[44:47]
	v_mfma_f32_16x16x32_bf16 v[40:43], v[132:135], v[206:209], v[40:43]
	v_mfma_f32_16x16x32_bf16 v[36:39], v[140:143], v[206:209], v[36:39]
	v_mfma_f32_16x16x32_bf16 v[64:67], v[136:139], v[186:189], v[64:67]
	v_mfma_f32_16x16x32_bf16 v[60:63], v[144:147], v[186:189], v[60:63]
	v_mfma_f32_16x16x32_bf16 v[56:59], v[136:139], v[194:197], v[56:59]
	v_mfma_f32_16x16x32_bf16 v[52:55], v[144:147], v[194:197], v[52:55]
	v_mfma_f32_16x16x32_bf16 v[48:51], v[136:139], v[202:205], v[48:51]
	v_mfma_f32_16x16x32_bf16 v[44:47], v[144:147], v[202:205], v[44:47]
	v_mfma_f32_16x16x32_bf16 v[40:43], v[136:139], v[210:213], v[40:43]
	v_mfma_f32_16x16x32_bf16 v[36:39], v[144:147], v[210:213], v[36:39]
	v_mfma_f32_16x16x32_bf16 v[32:35], v[148:151], v[182:185], v[32:35]
	v_mfma_f32_16x16x32_bf16 v[28:31], v[156:159], v[182:185], v[28:31]
	v_mfma_f32_16x16x32_bf16 v[24:27], v[148:151], v[190:193], v[24:27]
	v_mfma_f32_16x16x32_bf16 v[20:23], v[156:159], v[190:193], v[20:23]
	v_mfma_f32_16x16x32_bf16 v[16:19], v[148:151], v[198:201], v[16:19]
	v_mfma_f32_16x16x32_bf16 v[12:15], v[156:159], v[198:201], v[12:15]
	v_mfma_f32_16x16x32_bf16 v[8:11], v[148:151], v[206:209], v[8:11]
	v_mfma_f32_16x16x32_bf16 v[2:5], v[156:159], v[206:209], v[4:7]
	v_mfma_f32_16x16x32_bf16 v[32:35], v[152:155], v[186:189], v[32:35]
	v_mfma_f32_16x16x32_bf16 v[28:31], v[160:163], v[186:189], v[28:31]
	v_mfma_f32_16x16x32_bf16 v[24:27], v[152:155], v[194:197], v[24:27]
	v_mfma_f32_16x16x32_bf16 v[20:23], v[160:163], v[194:197], v[20:23]
	v_mfma_f32_16x16x32_bf16 v[16:19], v[152:155], v[202:205], v[16:19]
	v_mfma_f32_16x16x32_bf16 v[12:15], v[160:163], v[202:205], v[12:15]
	v_mfma_f32_16x16x32_bf16 v[8:11], v[152:155], v[210:213], v[8:11]
	v_mfma_f32_16x16x32_bf16 v[2:5], v[160:163], v[210:213], v[2:5]
	s_barrier
; #define PG8_STAGE(bufoff, gbase, voff) do { _Pragma("unroll") for (int _i = 0; _i < 2; ++_i) \
;         __builtin_amdgcn_global_load_lds((const unsigned*)((const char*)(gbase) + (voff)[_i]), (PG8_LAS unsigned*)(lds + (bufoff) + ldsw + _i * 8192), 16, 0, 0); } while (0)
; #define PG8_LDA(dst, b, h) do { _Pragma("unroll") for (int m = 0; m < 4; ++m) _Pragma("unroll") for (int k = 0; k < 2; ++k) dst[m][k] = *(const PG8_LAS bf16x8*)(lds + PG8_SA(b, h) + aoff + m * 2048 + k * 1024); } while (0)
; #define PG8_LDB(dst, b, h) do { _Pragma("unroll") for (int n = 0; n < 2; ++n) _Pragma("unroll") for (int k = 0; k < 2; ++k) dst[n][k] = *(const PG8_LAS bf16x8*)(lds + PG8_SB(b, h) + boff + n * 2048 + k * 1024); } while (0)
; #define PG8_WAIT_V(n) asm volatile("s_waitcnt vmcnt(" #n ")" ::: "memory")
; #define PG8_WAIT_L(n) asm volatile("s_waitcnt lgkmcnt(" #n ")" ::: "memory")
; #define PG8_BAR __builtin_amdgcn_s_barrier()
; #define PG8_SCHED __builtin_amdgcn_sched_barrier(0)
; template <class Epi, class Sched, bool ALIGN_EPI = false, bool SP2 = false, bool F8 = false>
; __device__ __forceinline__ void gemm_phase(PG8_LAS unsigned char* lds, const int K, const Sched& S, const Epi& E, const int wave) {
;     ...
;             PG8_LDB(B0, 1, 0); PG8_LDB(B1, 1, 1); PG8_SCHED; PG8_LDA(At, 1, 0); PG8_STAGE(PG8_SA(0, 1), a2 + hstep, voffA);
;             PG8_WAIT_V(8); PG8_WAIT_L(0); PG8_BAR; PG8_MMA(0, 0, At, B0); PG8_MMA(0, 1, At, B1); PG8_BAR; PG8_SCHED;
;             PG8_LDA(At, 1, 1); PG8_STAGE(PG8_SB(1, 0), b3, voffB); PG8_STAGE(PG8_SB(1, 1), b3 + hstep, voffB); PG8_STAGE(PG8_SA(1, 0), a3, voffA);
;             PG8_WAIT_V(8); PG8_WAIT_L(0); PG8_BAR; PG8_MMA(1, 0, At, B0); PG8_MMA(1, 1, At, B1); PG8_BAR; PG8_SCHED;
	s_setprio 0
	s_add_i32 s62, 0, 0x18000
	v_add_u32_e32 v1, s62, v220
	s_add_i32 s63, 0, 0x1c000
	ds_read_b128 v[132:135], v1
	ds_read_b128 v[136:139], v1 offset:1024
	ds_read_b128 v[140:143], v1 offset:2048
	ds_read_b128 v[144:147], v1 offset:3072
	v_add_u32_e32 v1, s63, v220
	ds_read_b128 v[148:151], v1
	ds_read_b128 v[152:155], v1 offset:1024
	ds_read_b128 v[156:159], v1 offset:2048
	ds_read_b128 v[160:163], v1 offset:3072
	s_add_u32 s60, s60, 0x100000
	s_addc_u32 s61, s61, 0
	s_mov_b32 m0, s89
	ds_read_b128 v[182:185], v222 offset:32768
	ds_read_b128 v[186:189], v222 offset:33792
	ds_read_b128 v[190:193], v222 offset:34816
	ds_read_b128 v[194:197], v222 offset:35840
	ds_read_b128 v[198:201], v222 offset:36864
	ds_read_b128 v[202:205], v222 offset:37888
	ds_read_b128 v[206:209], v222 offset:38912
	ds_read_b128 v[210:213], v222 offset:39936
	global_load_lds_dwordx4 v164, s[60:61]
	s_mov_b32 m0, s90
	s_nop 0
	global_load_lds_dwordx4 v168, s[60:61]
	s_waitcnt vmcnt(8)
	s_waitcnt lgkmcnt(0)
	s_setprio 1
	s_barrier
	v_mfma_f32_16x16x32_bf16 v[128:131], v[132:135], v[182:185], v[128:131]
	v_mfma_f32_16x16x32_bf16 v[124:127], v[140:143], v[182:185], v[124:127]
	v_mfma_f32_16x16x32_bf16 v[120:123], v[132:135], v[190:193], v[120:123]
	v_mfma_f32_16x16x32_bf16 v[116:119], v[140:143], v[190:193], v[116:119]
	v_mfma_f32_16x16x32_bf16 v[112:115], v[132:135], v[198:201], v[112:115]
	v_mfma_f32_16x16x32_bf16 v[108:111], v[140:143], v[198:201], v[108:111]
	v_mfma_f32_16x16x32_bf16 v[104:107], v[132:135], v[206:209], v[104:107]
	v_mfma_f32_16x16x32_bf16 v[100:103], v[140:143], v[206:209], v[100:103]
	v_mfma_f32_16x16x32_bf16 v[128:131], v[136:139], v[186:189], v[128:131]
	v_mfma_f32_16x16x32_bf16 v[124:127], v[144:147], v[186:189], v[124:127]
	v_mfma_f32_16x16x32_bf16 v[120:123], v[136:139], v[194:197], v[120:123]
	v_mfma_f32_16x16x32_bf16 v[116:119], v[144:147], v[194:197], v[116:119]
	v_mfma_f32_16x16x32_bf16 v[112:115], v[136:139], v[202:205], v[112:115]
	v_mfma_f32_16x16x32_bf16 v[108:111], v[144:147], v[202:205], v[108:111]
	v_mfma_f32_16x16x32_bf16 v[104:107], v[136:139], v[210:213], v[104:107]
	v_mfma_f32_16x16x32_bf16 v[100:103], v[144:147], v[210:213], v[100:103]
	v_mfma_f32_16x16x32_bf16 v[96:99], v[148:151], v[182:185], v[96:99]
	v_mfma_f32_16x16x32_bf16 v[92:95], v[156:159], v[182:185], v[92:95]
	v_mfma_f32_16x16x32_bf16 v[88:91], v[148:151], v[190:193], v[88:91]
	v_mfma_f32_16x16x32_bf16 v[84:87], v[156:159], v[190:193], v[84:87]
	v_mfma_f32_16x16x32_bf16 v[80:83], v[148:151], v[198:201], v[80:83]
	v_mfma_f32_16x16x32_bf16 v[76:79], v[156:159], v[198:201], v[76:79]
	v_mfma_f32_16x16x32_bf16 v[72:75], v[148:151], v[206:209], v[72:75]
	v_mfma_f32_16x16x32_bf16 v[68:71], v[156:159], v[206:209], v[68:71]
	v_mfma_f32_16x16x32_bf16 v[96:99], v[152:155], v[186:189], v[96:99]
	v_mfma_f32_16x16x32_bf16 v[92:95], v[160:163], v[186:189], v[92:95]
	v_mfma_f32_16x16x32_bf16 v[88:91], v[152:155], v[194:197], v[88:91]
	v_mfma_f32_16x16x32_bf16 v[84:87], v[160:163], v[194:197], v[84:87]
	v_mfma_f32_16x16x32_bf16 v[80:83], v[152:155], v[202:205], v[80:83]
	v_mfma_f32_16x16x32_bf16 v[76:79], v[160:163], v[202:205], v[76:79]
	v_mfma_f32_16x16x32_bf16 v[72:75], v[152:155], v[210:213], v[72:75]
	v_mfma_f32_16x16x32_bf16 v[68:71], v[160:163], v[210:213], v[68:71]
	s_barrier
	s_setprio 0
	s_add_i32 s60, s62, s86
	s_mov_b32 m0, s60
	ds_read_b128 v[182:185], v222 offset:49152
	ds_read_b128 v[186:189], v222 offset:50176
	ds_read_b128 v[190:193], v222 offset:51200
	ds_read_b128 v[194:197], v222 offset:52224
	ds_read_b128 v[198:201], v222 offset:53248
	ds_read_b128 v[202:205], v222 offset:54272
	ds_read_b128 v[206:209], v222 offset:55296
	ds_read_b128 v[210:213], v222 offset:56320
	global_load_lds_dwordx4 v166, s[58:59]
	s_add_i32 m0, s60, 0x2000
	s_nop 0
	global_load_lds_dwordx4 v170, s[58:59]
	s_add_u32 s58, s58, 0x100000
	s_addc_u32 s59, s59, 0
	s_add_i32 s60, s63, s86
	s_mov_b32 m0, s60
	s_nop 0
	global_load_lds_dwordx4 v166, s[58:59]
	s_add_i32 m0, s60, 0x2000
	s_nop 0
	global_load_lds_dwordx4 v170, s[58:59]
	s_mov_b32 m0, s79
	s_nop 0
	global_load_lds_dwordx4 v164, s[56:57]
	s_mov_b32 m0, s80
	s_nop 0
	global_load_lds_dwordx4 v168, s[56:57]
	s_waitcnt vmcnt(8)
	s_waitcnt lgkmcnt(0)
	s_setprio 1
	s_barrier
	v_mfma_f32_16x16x32_bf16 v[64:67], v[132:135], v[182:185], v[64:67]
	v_mfma_f32_16x16x32_bf16 v[60:63], v[140:143], v[182:185], v[60:63]
	v_mfma_f32_16x16x32_bf16 v[56:59], v[132:135], v[190:193], v[56:59]
	v_mfma_f32_16x16x32_bf16 v[52:55], v[140:143], v[190:193], v[52:55]
	v_mfma_f32_16x16x32_bf16 v[48:51], v[132:135], v[198:201], v[48:51]
	v_mfma_f32_16x16x32_bf16 v[44:47], v[140:143], v[198:201], v[44:47]
	v_mfma_f32_16x16x32_bf16 v[40:43], v[132:135], v[206:209], v[40:43]
	v_mfma_f32_16x16x32_bf16 v[36:39], v[140:143], v[206:209], v[36:39]
	v_mfma_f32_16x16x32_bf16 v[64:67], v[136:139], v[186:189], v[64:67]
	v_mfma_f32_16x16x32_bf16 v[60:63], v[144:147], v[186:189], v[60:63]
	v_mfma_f32_16x16x32_bf16 v[56:59], v[136:139], v[194:197], v[56:59]
	v_mfma_f32_16x16x32_bf16 v[52:55], v[144:147], v[194:197], v[52:55]
	v_mfma_f32_16x16x32_bf16 v[48:51], v[136:139], v[202:205], v[48:51]
	v_mfma_f32_16x16x32_bf16 v[44:47], v[144:147], v[202:205], v[44:47]
	v_mfma_f32_16x16x32_bf16 v[40:43], v[136:139], v[210:213], v[40:43]
	v_mfma_f32_16x16x32_bf16 v[36:39], v[144:147], v[210:213], v[36:39]
	v_mfma_f32_16x16x32_bf16 v[32:35], v[148:151], v[182:185], v[32:35]
	v_mfma_f32_16x16x32_bf16 v[28:31], v[156:159], v[182:185], v[28:31]
	v_mfma_f32_16x16x32_bf16 v[24:27], v[148:151], v[190:193], v[24:27]
	v_mfma_f32_16x16x32_bf16 v[20:23], v[156:159], v[190:193], v[20:23]
	v_mfma_f32_16x16x32_bf16 v[16:19], v[148:151], v[198:201], v[16:19]
	v_mfma_f32_16x16x32_bf16 v[12:15], v[156:159], v[198:201], v[12:15]
	v_mfma_f32_16x16x32_bf16 v[6:9], v[148:151], v[206:209], v[8:11]
	v_mfma_f32_16x16x32_bf16 v[2:5], v[156:159], v[206:209], v[2:5]
	v_mfma_f32_16x16x32_bf16 v[32:35], v[152:155], v[186:189], v[32:35]
	v_mfma_f32_16x16x32_bf16 v[28:31], v[160:163], v[186:189], v[28:31]
	v_mfma_f32_16x16x32_bf16 v[24:27], v[152:155], v[194:197], v[24:27]
	v_mfma_f32_16x16x32_bf16 v[20:23], v[160:163], v[194:197], v[20:23]
	v_mfma_f32_16x16x32_bf16 v[16:19], v[152:155], v[202:205], v[16:19]
	v_mfma_f32_16x16x32_bf16 v[12:15], v[160:163], v[202:205], v[12:15]
	v_mfma_f32_16x16x32_bf16 v[8:11], v[152:155], v[210:213], v[6:9]
	v_mfma_f32_16x16x32_bf16 v[4:7], v[160:163], v[210:213], v[2:5]
	s_barrier
	s_setprio 0
	s_add_u32 s78, s78, 0x100
	s_addc_u32 s23, s23, 0
	s_add_u32 s72, s72, 0x100
	s_addc_u32 s8, s8, 0
	s_add_u32 s42, s42, 0x100
	s_addc_u32 s43, s43, 0
	s_cmp_ge_i32 s9, s85
	s_cbranch_scc1 .LBB0_773

;     __host__ __device__ bool next(int i, Unit& u) const {
;     ...
;                 int wgid = (int)L; { const int qq = nwg / NXCD, r = nwg % NXCD, xcd = wgid % NXCD, off = wgid / NXCD; wgid = (xcd < r ? xcd * (qq + 1) : r * (qq + 1) + (xcd - r) * qq) + off; }
;                 const int nig = WGM * nN, gid = wgid / nig, fm = gid * WGM, gsz = (nM - fm) < WGM ? (nM - fm) : WGM;
;                 u.pm = fm + ((wgid % nig) % gsz); u.pn = (wgid % nig) / gsz; u.prob = q;
;                 u.a = p[q].A + (size_t)u.pm * tstep; u.b = p[q].B + (size_t)u.pn * tstep; u.pm += p[q].pm0; u.pn += p[q].pn0; u.nt = p[q].nt; u.f8 = p[q].f8; return true; }
.LBB0_877:
.LBB0_878:
	s_and_b32 s6, s2, 7
	s_lshl_b32 s6, s6, 3
	s_bfe_u32 s7, s2, 0x30003
	s_or_b32 s84, s7, s6
	s_bfe_u32 s83, s2, 0x20006
	s_lshl_b32 s6, s84, 21
	v_readlane_b32 s7, v255, 3
	s_add_u32 s10, s7, s6
	v_readlane_b32 s6, v255, 46
	s_addc_u32 s11, s6, 0
	s_lshl_b32 s6, s83, 21
	s_add_u32 s12, s73, s6
	s_addc_u32 s13, s74, 0
	s_mov_b64 s[6:7], s[2:3]
	s_and_b64 vcc, exec, s[0:1]
	s_cbranch_vccz .LBB0_727
